# XCD-local seams v3: all seams from ph6 on are XCD-local (split post/check events keep the PROJ/ACT write-after-read order across XCDs), final norm rows re-mapped to the owning XCD
# speedup vs baseline: 1.0133x; 1.0133x over previous
; __device__ __forceinline__ unsigned xb_add(unsigned* p, unsigned v) { return __hip_atomic_fetch_add(p, v, __ATOMIC_RELAXED, __HIP_MEMORY_SCOPE_AGENT); }
; __device__ __forceinline__ void xcd_barrier(const XcdBarrier& b) {
;     ...
;         if (old + 1u == (gen + 1u) * nloc) {
;             __builtin_amdgcn_fence(__ATOMIC_RELEASE, "agent");
;             asm volatile("s_waitcnt vmcnt(0)" ::: "memory");
;             const unsigned og = xb_add(&bar[XB_TOP], 1u);
;             const unsigned tg = og / nx;
;             if (og + 1u == (tg + 1u) * nx) xb_add(&bar[XB_TOPGEN], 1u);
.LBB0_660:
	s_andn2_saveexec_b64 s[0:1], s[8:9]
	s_cbranch_execz .LBB0_680
	s_mov_b64 s[8:9], exec
	s_cmp_eq_u32 s101, 1
	s_cbranch_scc0 .Lxf_0
	s_branch .LBB0_677
.Lxf_0:
	buffer_wbl2 sc1
	s_waitcnt lgkmcnt(0)
	s_waitcnt vmcnt(0)
	v_mbcnt_lo_u32_b32 v2, s8, 0
	v_mbcnt_hi_u32_b32 v2, s9, v2
	v_cmp_eq_u32_e32 vcc, 0, v2
	s_and_saveexec_b64 s[10:11], vcc
	s_cbranch_execz .LBB0_663
	s_bcnt1_i32_b64 s0, s[8:9]
	v_mov_b32_e32 v3, 0x7000
	v_mov_b32_e32 v4, s0
	global_atomic_add v3, v3, v4, s[78:79] offset:1024 sc0

; __device__ __forceinline__ unsigned xb_add(unsigned* p, unsigned v) { return __hip_atomic_fetch_add(p, v, __ATOMIC_RELAXED, __HIP_MEMORY_SCOPE_AGENT); }
; __device__ __forceinline__ void xcd_barrier(const XcdBarrier& b) {
;     ...
;         if (old + 1u == (gen + 1u) * nloc) {
;             __builtin_amdgcn_fence(__ATOMIC_RELEASE, "agent");
;             asm volatile("s_waitcnt vmcnt(0)" ::: "memory");
;             const unsigned og = xb_add(&bar[XB_TOP], 1u);
;             const unsigned tg = og / nx;
;             if (og + 1u == (tg + 1u) * nx) xb_add(&bar[XB_TOPGEN], 1u);
.LBB0_861:
	s_andn2_saveexec_b64 s[0:1], s[8:9]
	s_cbranch_execz .LBB0_881
	s_mov_b64 s[8:9], exec
	s_cmp_eq_u32 s101, 1
	s_cbranch_scc0 .Lxf_2
	s_add_u32 s98, s78, 0x4140
	s_addc_u32 s99, s79, 0
	v_mov_b32_e32 v2, 0
	v_mov_b32_e32 v3, 1
	global_atomic_add v2, v3, s[98:99]
	s_branch .LBB0_878

; __device__ __forceinline__ unsigned xb_add(unsigned* p, unsigned v) { return __hip_atomic_fetch_add(p, v, __ATOMIC_RELAXED, __HIP_MEMORY_SCOPE_AGENT); }
; __device__ __forceinline__ void xcd_barrier(const XcdBarrier& b) {
;     asm volatile("s_waitcnt vmcnt(0)" ::: "memory");
;     __syncthreads();
;     if (threadIdx.x == 0) {
;         unsigned* bar = b.bar;
;         __builtin_amdgcn_s_waitcnt(0);
;         unsigned nloc = b.st[0], nx = b.st[1];
;         if (nloc == 0u) { xcd_barrier_complete(bar, b.x, nloc, nx); b.st[0] = nloc; b.st[1] = nx; }
;         const unsigned old = xb_add(&bar[XB_XSUB(b.x)], 1u);
.LBB0_926:
	s_waitcnt vmcnt(0)
	s_waitcnt vmcnt(0) lgkmcnt(0)
	s_barrier
	s_mov_b64 s[4:5], exec
	v_readlane_b32 s0, v254, 1
	v_readlane_b32 s1, v254, 2
	s_and_b64 s[0:1], s[4:5], s[0:1]
	s_mov_b64 exec, s[0:1]
	s_cbranch_execz .LBB0_978
	s_add_i32 s0, 0, 0x20000
	v_mov_b32_e32 v1, s0
	s_waitcnt vmcnt(0) expcnt(0) lgkmcnt(0)
	ds_read_b32 v3, v1
	s_add_i32 s0, 0, 0x20004
	v_mov_b32_e32 v1, s0
	ds_read_b32 v1, v1
	v_mov_b32_e32 v2, 0x20008
	ds_read_b32 v2, v2
	s_waitcnt lgkmcnt(0)
	v_readfirstlane_b32 s101, v2
	s_cmp_eq_u32 s101, 1
	s_cbranch_scc0 .Lxm_3
	buffer_inv sc1

; __device__ __forceinline__ unsigned xb_ld(unsigned* p)              { return __hip_atomic_load(p, __ATOMIC_RELAXED, __HIP_MEMORY_SCOPE_AGENT); }
; __device__ __forceinline__ unsigned xb_add(unsigned* p, unsigned v) { return __hip_atomic_fetch_add(p, v, __ATOMIC_RELAXED, __HIP_MEMORY_SCOPE_AGENT); }
; #define XB_SPIN(cond, bar) do { unsigned _sp = 0; while (cond) { __builtin_amdgcn_s_sleep(1); \
;     if ((++_sp & 255u) == 0u) { if (xb_ld(&(bar)[XB_TMO])) break; if (_sp > XB_SPIN_CAP) { atomicAdd(&(bar)[XB_TMO], 1u); break; } } } } while (0)
; __device__ __forceinline__ void xcd_barrier(const XcdBarrier& b) {
;     ...
;         const unsigned old = xb_add(&bar[XB_XSUB(b.x)], 1u);
;         const unsigned gen = old / nloc;
;         if (old + 1u == (gen + 1u) * nloc) {
;             __builtin_amdgcn_fence(__ATOMIC_RELEASE, "agent");
;             asm volatile("s_waitcnt vmcnt(0)" ::: "memory");
;             const unsigned og = xb_add(&bar[XB_TOP], 1u);
;             const unsigned tg = og / nx;
;             if (og + 1u == (tg + 1u) * nx) xb_add(&bar[XB_TOPGEN], 1u);
;             else XB_SPIN(xb_ld(&bar[XB_TOPGEN]) == tg, bar);
;             __builtin_amdgcn_fence(__ATOMIC_ACQUIRE, "agent");
;             xb_add(&bar[XB_XGEN(b.x)], 1u);
;             asm volatile("s_waitcnt vmcnt(0)" ::: "memory");
;         } else {
;             XB_SPIN(xb_ld(&bar[XB_XGEN(b.x)]) == gen, bar);
.LBB0_958:
	s_andn2_saveexec_b64 s[0:1], s[8:9]
	s_cbranch_execz .LBB0_978
	s_mov_b64 s[8:9], exec
	s_cmp_eq_u32 s101, 1
	s_cbranch_scc0 .Lxf_3
	s_add_u32 s98, s78, 0x4140
	s_addc_u32 s99, s79, 0
	v_mov_b32_e32 v2, 0
	s_mov_b32 s100, 0
.Lxc_3:
	global_load_dword v3, v2, s[98:99] sc1
	s_waitcnt vmcnt(0)
	v_cmp_eq_u32_e32 vcc, v3, v1
	s_cbranch_vccnz .Lxd_3
	s_sleep 1
	s_add_u32 s100, s100, 1
	s_cmp_lt_u32 s100, 0x100000
	s_cbranch_scc1 .Lxc_3

; __device__ __forceinline__ unsigned xb_add(unsigned* p, unsigned v) { return __hip_atomic_fetch_add(p, v, __ATOMIC_RELAXED, __HIP_MEMORY_SCOPE_AGENT); }
; __device__ __forceinline__ void xcd_barrier(const XcdBarrier& b) {
;     ...
;         if (old + 1u == (gen + 1u) * nloc) {
;             __builtin_amdgcn_fence(__ATOMIC_RELEASE, "agent");
;             asm volatile("s_waitcnt vmcnt(0)" ::: "memory");
;             const unsigned og = xb_add(&bar[XB_TOP], 1u);
;             const unsigned tg = og / nx;
;             if (og + 1u == (tg + 1u) * nx) xb_add(&bar[XB_TOPGEN], 1u);
.LBB0_1425:
	s_andn2_saveexec_b64 s[0:1], s[8:9]
	s_cbranch_execz .LBB0_1445
	s_mov_b64 s[8:9], exec
	s_cmp_eq_u32 s101, 1
	s_cbranch_scc0 .Lxf_5
	s_add_u32 s98, s78, 0x4180
	s_addc_u32 s99, s79, 0
	v_mov_b32_e32 v2, 0
	v_mov_b32_e32 v3, 1
	global_atomic_add v2, v3, s[98:99]
	s_branch .LBB0_1442

; __device__ __forceinline__ unsigned xb_ld(unsigned* p)              { return __hip_atomic_load(p, __ATOMIC_RELAXED, __HIP_MEMORY_SCOPE_AGENT); }
; __device__ __forceinline__ unsigned xb_add(unsigned* p, unsigned v) { return __hip_atomic_fetch_add(p, v, __ATOMIC_RELAXED, __HIP_MEMORY_SCOPE_AGENT); }
; #define XB_SPIN(cond, bar) do { unsigned _sp = 0; while (cond) { __builtin_amdgcn_s_sleep(1); \
;     if ((++_sp & 255u) == 0u) { if (xb_ld(&(bar)[XB_TMO])) break; if (_sp > XB_SPIN_CAP) { atomicAdd(&(bar)[XB_TMO], 1u); break; } } } } while (0)
; __device__ __forceinline__ void xcd_barrier(const XcdBarrier& b) {
;     ...
;         const unsigned old = xb_add(&bar[XB_XSUB(b.x)], 1u);
;         const unsigned gen = old / nloc;
;         if (old + 1u == (gen + 1u) * nloc) {
;             __builtin_amdgcn_fence(__ATOMIC_RELEASE, "agent");
;             asm volatile("s_waitcnt vmcnt(0)" ::: "memory");
;             const unsigned og = xb_add(&bar[XB_TOP], 1u);
;             const unsigned tg = og / nx;
;             if (og + 1u == (tg + 1u) * nx) xb_add(&bar[XB_TOPGEN], 1u);
;             else XB_SPIN(xb_ld(&bar[XB_TOPGEN]) == tg, bar);
;             __builtin_amdgcn_fence(__ATOMIC_ACQUIRE, "agent");
;             xb_add(&bar[XB_XGEN(b.x)], 1u);
;             asm volatile("s_waitcnt vmcnt(0)" ::: "memory");
;         } else {
;             XB_SPIN(xb_ld(&bar[XB_XGEN(b.x)]) == gen, bar);
.LBB0_1522:
	s_andn2_saveexec_b64 s[0:1], s[8:9]
	s_cbranch_execz .LBB0_1542
	s_mov_b64 s[8:9], exec
	s_cmp_eq_u32 s101, 1
	s_cbranch_scc0 .Lxf_6
	s_add_u32 s98, s78, 0x4180
	s_addc_u32 s99, s79, 0
	v_mov_b32_e32 v2, 0
	s_mov_b32 s100, 0

; __device__ __forceinline__ float bflo(unsigned w) { return __uint_as_float(w << 16); }
; __device__ __forceinline__ float bfhi(unsigned w) { return __uint_as_float(w & 0xffff0000u); }
; __device__ __forceinline__ void final_norm_phase(const Frame& F, const bf16* h, const float* ssq, const float* gain, float* out) {
;     for (int it = F.bx * NTHR + F.tid; it < M * 128; it += F.G * NTHR) { const int row = it >> 7, c8 = (it & 127) * 8; const float rs = rstd_row(ssq, row);
;         const v4u w = *(const v4u*)(h + (size_t)row * DM_ + c8); const f32x4 g0 = *(const f32x4*)(gain + c8), g1 = *(const f32x4*)(gain + c8 + 4);
;         float* o = out + (size_t)row * DM_ + c8;
;         __builtin_nontemporal_store((f32x4){bflo(w.x) * rs * g0[0], bfhi(w.x) * rs * g0[1], bflo(w.y) * rs * g0[2], bfhi(w.y) * rs * g0[3]}, (f32x4*)o);
;         __builtin_nontemporal_store((f32x4){bflo(w.z) * rs * g1[0], bfhi(w.z) * rs * g1[1], bflo(w.w) * rs * g1[2], bfhi(w.w) * rs * g1[3]}, (f32x4*)(o + 4)); }
; }
.LBB0_1841:
	s_cmp_lt_i32 s80, 18
	s_cselect_b64 s[0:1], -1, 0
	s_cmp_gt_i32 s81, 17
	s_cselect_b64 s[2:3], -1, 0
	s_and_b64 s[0:1], s[0:1], s[2:3]
	s_andn2_b64 vcc, exec, s[0:1]
	s_cbranch_vccnz .LBB0_1845
	s_mov_b32 s0, 0x400000
	s_lshl_b32 s98, s96, 9
	s_cmp_eq_u32 s82, 0x100
	s_cbranch_scc0 .Lfn_g
	s_and_b32 s98, s96, 7
	s_lshl_b32 s98, s98, 19
	s_lshr_b32 s99, s96, 3
	s_lshl_b32 s99, s99, 14
	s_or_b32 s98, s98, s99
.Lfn_g:
	v_add_u32_e32 v2, s98, v0
	s_mov_b32 s8, 28
	v_cmp_gt_i32_e32 vcc, s0, v2
	s_and_saveexec_b64 s[0:1], vcc
	s_cbranch_execz .LBB0_1845
	s_waitcnt lgkmcnt(0)
	s_add_u32 s4, s78, 0x7c00000
	s_addc_u32 s5, s79, 0
	s_add_u32 s6, s78, 0x5800000
	s_addc_u32 s7, s79, 0
	s_ashr_i32 s9, s8, 31
	s_lshl_b64 s[0:1], s[8:9], 3
	s_add_u32 s0, s74, s0
	s_addc_u32 s1, s75, s1
	s_load_dwordx2 s[0:1], s[0:1], 0x0
	v_lshlrev_b32_e32 v0, 3, v0
	s_lshl_b32 s8, s82, 9
	s_cmp_eq_u32 s82, 0x100
	s_cselect_b32 s8, 0x200, s8
	v_lshlrev_b32_e32 v3, 3, v2
	s_lshl_b32 s9, s8, 3
	s_mov_b64 s[2:3], 0
	v_mov_b32_e32 v4, 0x358637bd
	v_mov_b32_e32 v1, 0
	s_mov_b32 s10, 0x3fffff
	s_cmp_eq_u32 s82, 0x100
	s_cbranch_scc0 .Lfn_b
	s_add_u32 s10, s98, 0x3fff
.Lfn_b:
.LBB0_1844:
	v_ashrrev_i32_e32 v34, 7, v2
	v_ashrrev_i32_e32 v35, 31, v34
	v_lshlrev_b64 v[6:7], 6, v[34:35]
	v_lshlrev_b64 v[8:9], 11, v[34:35]
	v_lshl_add_u64 v[22:23], s[6:7], 0, v[6:7]
	v_lshl_add_u64 v[24:25], s[4:5], 0, v[8:9]
	global_load_dwordx4 v[6:9], v[22:23], off
	global_load_dwordx4 v[10:13], v[22:23], off offset:32
	global_load_dwordx4 v[14:17], v[22:23], off offset:16
	global_load_dwordx4 v[18:21], v[22:23], off offset:48
	v_and_b32_e32 v5, 0x3f8, v3
	v_lshlrev_b32_e32 v0, 1, v5
	v_lshl_add_u64 v[36:37], v[24:25], 0, v[0:1]
	v_lshlrev_b32_e32 v0, 2, v5
	global_load_dwordx4 v[22:25], v[36:37], off
	s_waitcnt lgkmcnt(0)
	global_load_dwordx4 v[26:29], v0, s[0:1]
	global_load_dwordx4 v[30:33], v0, s[0:1] offset:16
	v_lshlrev_b64 v[34:35], 12, v[34:35]
	v_lshl_add_u64 v[34:35], s[76:77], 0, v[34:35]
	v_lshl_add_u64 v[34:35], v[34:35], 0, v[0:1]
	v_add_u32_e32 v2, s8, v2
	v_cmp_lt_i32_e32 vcc, s10, v2
	v_add_u32_e32 v3, s9, v3
	s_or_b64 s[2:3], vcc, s[2:3]
	s_waitcnt vmcnt(0)
	v_mov_b32_e32 v36, v6
	v_mov_b32_e32 v37, v10
	v_mov_b32_e32 v10, v7
	v_mov_b32_e32 v6, v8
	v_mov_b32_e32 v7, v12
	v_mov_b32_e32 v12, v9
	v_mov_b32_e32 v8, v14
	v_mov_b32_e32 v9, v18
	v_mov_b32_e32 v18, v15
	v_mov_b32_e32 v14, v16
	v_mov_b32_e32 v15, v20
	v_mov_b32_e32 v20, v17
	v_pk_add_f32 v[10:11], v[36:37], v[10:11]
	v_pk_add_f32 v[6:7], v[6:7], v[12:13]
	v_pk_add_f32 v[8:9], v[8:9], v[18:19]
	v_pk_add_f32 v[12:13], v[14:15], v[20:21]
	v_pk_add_f32 v[6:7], v[10:11], v[6:7]
	v_pk_add_f32 v[8:9], v[8:9], v[12:13]
	v_lshlrev_b32_e32 v14, 16, v22
	v_pk_add_f32 v[6:7], v[6:7], v[8:9]
	v_and_b32_e32 v15, 0xffff0000, v22
	v_add_f32_e32 v0, v6, v7
	v_fmamk_f32 v0, v0, 0x3a800000, v4
	v_rsq_f32_e32 v0, v0
	v_lshlrev_b32_e32 v16, 16, v23
	v_and_b32_e32 v17, 0xffff0000, v23
	v_lshlrev_b32_e32 v18, 16, v24
	v_and_b32_e32 v19, 0xffff0000, v24
	v_lshlrev_b32_e32 v20, 16, v25
	v_and_b32_e32 v21, 0xffff0000, v25
	v_pk_mul_f32 v[6:7], v[0:1], v[14:15] op_sel_hi:[0,1]
	v_pk_mul_f32 v[8:9], v[0:1], v[16:17] op_sel_hi:[0,1]
	v_pk_mul_f32 v[10:11], v[0:1], v[18:19] op_sel_hi:[0,1]
	v_pk_mul_f32 v[12:13], v[0:1], v[20:21] op_sel_hi:[0,1]
	v_pk_mul_f32 v[6:7], v[26:27], v[6:7]
	v_pk_mul_f32 v[8:9], v[28:29], v[8:9]
	v_pk_mul_f32 v[10:11], v[30:31], v[10:11]
	v_pk_mul_f32 v[12:13], v[32:33], v[12:13]
	global_store_dwordx4 v[34:35], v[6:9], off nt
	global_store_dwordx4 v[34:35], v[10:13], off offset:16 nt
	s_andn2_b64 exec, exec, s[2:3]
	s_cbranch_execnz .LBB0_1844
